# strategy: prologue de-serialisation - attention block bias fill issues its up-to-four loads together and waits once instead of load-wait-store per 2048 keys
# speedup vs baseline: 1.0044x; 1.0037x over previous
; __device__ __forceinline__ void block(const BlockRef& cur, const BlockRef& nxt, char* lds, Seam& S) {
;     ...
;     { const float cref = cur.C[cur.P0]; const int n4 = (cur.P0 + QB) >> 2; int tl = threadIdx.x; asm volatile("" : "+v"(tl));
;       for (int i = tl; i < n4; i += 512) { const f32x4 c4 = *(const f32x4*)(cur.C + 4 * i); *(f32x4*)(bias + 4 * i) = (cref - c4) * INV_SCALE; } }
.LBB0_1122:
	s_add_i32 s43, s56, 0x100
	s_lshl_b64 s[6:7], s[56:57], 2
	s_add_u32 s6, s22, s6
	v_mov_b32_e32 v174, v182
	s_addc_u32 s7, s23, s7
	global_load_dword v2, v161, s[6:7]
	s_lshr_b32 s44, s43, 2
	v_mov_b32_e32 v3, v182
	v_readfirstlane_b32 s66, v174
	s_nop 0
	v_cmp_gt_i32_e32 vcc, s44, v3
	s_and_saveexec_b64 s[6:7], vcc
	s_cbranch_execz .LBB0_1125
	v_lshl_add_u32 v4, v3, 4, s63
	v_lshlrev_b32_e32 v0, 2, v3
	v_mov_b32_e32 v1, 0
	s_mov_b64 s[100:101], exec
	v_lshl_add_u64 v[6:7], v[0:1], 2, s[22:23]
	global_load_dwordx4 v[128:131], v[6:7], off
	v_add_u32_e32 v5, 0x200, v3
	v_cmp_gt_i32_e32 vcc, s44, v5
	s_and_b64 exec, exec, vcc
	s_cbranch_execz .Lbf_wait
	s_add_u32 s8, s22, 0x2000
	s_addc_u32 s9, s23, 0
	v_lshl_add_u64 v[6:7], v[0:1], 2, s[8:9]
	global_load_dwordx4 v[132:135], v[6:7], off
	v_add_u32_e32 v5, 0x400, v3
	v_cmp_gt_i32_e32 vcc, s44, v5
	s_and_b64 exec, exec, vcc
	s_cbranch_execz .Lbf_wait
	s_add_u32 s8, s22, 0x4000
	s_addc_u32 s9, s23, 0
	v_lshl_add_u64 v[6:7], v[0:1], 2, s[8:9]
	global_load_dwordx4 v[136:139], v[6:7], off
	v_add_u32_e32 v5, 0x600, v3
	v_cmp_gt_i32_e32 vcc, s44, v5
	s_and_b64 exec, exec, vcc
	s_cbranch_execz .Lbf_wait
	s_add_u32 s8, s22, 0x6000
	s_addc_u32 s9, s23, 0
	v_lshl_add_u64 v[6:7], v[0:1], 2, s[8:9]
	global_load_dwordx4 v[140:143], v[6:7], off
.Lbf_wait:
	s_mov_b64 exec, s[100:101]
	s_waitcnt vmcnt(0)
	v_sub_f32_e32 v129, v2, v129
	v_sub_f32_e32 v128, v2, v128
	v_sub_f32_e32 v131, v2, v131
	v_sub_f32_e32 v130, v2, v130
	v_pk_mul_f32 v[130:131], v[130:131], s[24:25] op_sel_hi:[1,0]
	v_pk_mul_f32 v[128:129], v[128:129], s[24:25] op_sel_hi:[1,0]
	ds_write_b128 v4, v[128:131]
	v_add_u32_e32 v5, 0x200, v3
	v_cmp_gt_i32_e32 vcc, s44, v5
	s_and_b64 exec, exec, vcc
	s_cbranch_execz .Lbf_done
	v_sub_f32_e32 v133, v2, v133
	v_sub_f32_e32 v132, v2, v132
	v_sub_f32_e32 v135, v2, v135
	v_sub_f32_e32 v134, v2, v134
	v_pk_mul_f32 v[134:135], v[134:135], s[24:25] op_sel_hi:[1,0]
	v_pk_mul_f32 v[132:133], v[132:133], s[24:25] op_sel_hi:[1,0]
	ds_write_b128 v4, v[132:135] offset:8192
	v_add_u32_e32 v5, 0x400, v3
	v_cmp_gt_i32_e32 vcc, s44, v5
	s_and_b64 exec, exec, vcc
	s_cbranch_execz .Lbf_done
	v_sub_f32_e32 v137, v2, v137
	v_sub_f32_e32 v136, v2, v136
	v_sub_f32_e32 v139, v2, v139
	v_sub_f32_e32 v138, v2, v138
	v_pk_mul_f32 v[138:139], v[138:139], s[24:25] op_sel_hi:[1,0]
	v_pk_mul_f32 v[136:137], v[136:137], s[24:25] op_sel_hi:[1,0]
	ds_write_b128 v4, v[136:139] offset:16384
	v_add_u32_e32 v5, 0x600, v3
	v_cmp_gt_i32_e32 vcc, s44, v5
	s_and_b64 exec, exec, vcc
	s_cbranch_execz .Lbf_done
	v_sub_f32_e32 v141, v2, v141
	v_sub_f32_e32 v140, v2, v140
	v_sub_f32_e32 v143, v2, v143
	v_sub_f32_e32 v142, v2, v142
	v_pk_mul_f32 v[142:143], v[142:143], s[24:25] op_sel_hi:[1,0]
	v_pk_mul_f32 v[140:141], v[140:141], s[24:25] op_sel_hi:[1,0]
	ds_write_b128 v4, v[140:143] offset:24576
.Lbf_done:
.LBB0_1125:
	s_or_b64 exec, exec, s[6:7]
	s_lshr_b32 s58, s43, 6
	v_and_b32_e32 v175, 63, v174
	s_cmp_lt_u32 s66, 64
	s_waitcnt lgkmcnt(0)
	s_barrier
	s_cbranch_scc0 .LBB0_1133
	v_fmaak_f32 v0, 2.0, v172, 0x42380000
	v_mul_f32_e32 v0, 0xc13504f3, v0
	v_cmp_gt_u32_e32 vcc, s58, v175
	s_mov_b64 s[6:7], 0
	s_mov_b64 s[8:9], 0
	s_and_saveexec_b64 s[44:45], vcc
	s_cbranch_execz .LBB0_1128
	v_lshl_add_u32 v1, v175, 8, s63
	ds_read_b32 v1, v1 offset:252
	s_waitcnt lgkmcnt(0)
	v_cmp_lt_f32_e32 vcc, v1, v0
	s_and_b64 s[8:9], vcc, exec
